# SrcC-fold attention loop on the variant that also hoists the mid-trip K fragment reads
# speedup vs baseline: 1.0040x; 1.0040x over previous
; #define MFMA(a, b, c) __builtin_amdgcn_mfma_f32_32x32x16_bf16((a), (b), (c), 0, 0, 0)
; DI float fexp2(float x) { return __builtin_amdgcn_exp2f(x); }
; DI void phase_attn(const Params& p, int hf, bool skipctx, char* smem, int& rot) {
;     ...
;       float ps = 0.f;
; #pragma unroll
;       for (int kb = 0; kb < 2; ++kb)
; #pragma unroll
;         for (int i = 0; i < 16; ++i) { const float e = fexp2(st[kb][i] - m_run); st[kb][i] = e; ps += e; }
;       l_run += ps;
; #pragma unroll
;       for (int kb = 0; kb < 2; ++kb)
; #pragma unroll
;         for (int s2 = 0; s2 < 2; ++s2) {
;           const bf16x8 pb = pack8(st[kb][8 * s2 + 0], st[kb][8 * s2 + 1], st[kb][8 * s2 + 2], st[kb][8 * s2 + 3], st[kb][8 * s2 + 4], st[kb][8 * s2 + 5], st[kb][8 * s2 + 6], st[kb][8 * s2 + 7]);
; #pragma unroll
;           for (int dvb = 0; dvb < 2; ++dvb) o[dvb] = MFMA(vf[kb][s2][dvb], pb, o[dvb]);
;         }
;     };
;     __syncthreads();
;     ATT_LOAD(ak0, ak1, ak2, av0, av1, 0);
;     ATT_LOAD(bk0, bk1, bk2, bv0, bv1, 1);
;     ATT_WRITE(ak0, ak1, ak2, av0, av1, 0);
;     __syncthreads();
;     for (int kt = 0; kt < nkt; kt += 2) {
;       if (kt + 2 < nkt) ATT_LOAD(ak0, ak1, ak2, av0, av1, kt + 2);
;       compute(0, 0); compute(0, 1);
;       ATT_WRITE(bk0, bk1, bk2, bv0, bv1, 1);
;       __syncthreads();
;       if (kt + 3 < nkt) ATT_LOAD(bk0, bk1, bk2, bv0, bv1, kt + 3);
;       compute(1, 0); compute(1, 1);
.LBB0_801:
	v_exp_f32_e32 v48, v48
	v_exp_f32_e32 v49, v49
	v_exp_f32_e32 v50, v50
	v_exp_f32_e32 v51, v51
	v_exp_f32_e32 v52, v52
	v_exp_f32_e32 v53, v53
	v_exp_f32_e32 v54, v54
	v_exp_f32_e32 v55, v55
	v_cvt_pk_bf16_f32 v214, v48, v49
	v_cvt_pk_bf16_f32 v215, v50, v51
	v_cvt_pk_bf16_f32 v216, v52, v53
	v_cvt_pk_bf16_f32 v217, v54, v55
	s_waitcnt lgkmcnt(7)
	s_nop 0
	v_mfma_f32_32x32x16_bf16 v[16:31], v[156:159], v[214:217], v[16:31]
	v_exp_f32_e32 v56, v56
	s_waitcnt lgkmcnt(5)
	v_mfma_f32_32x32x16_bf16 v[0:15], v[152:155], v[214:217], v[0:15]
	v_exp_f32_e32 v57, v57
	v_exp_f32_e32 v58, v58
	v_exp_f32_e32 v59, v59
	v_exp_f32_e32 v60, v60
	v_exp_f32_e32 v61, v61
	v_exp_f32_e32 v62, v62
	v_exp_f32_e32 v63, v63
	v_cvt_pk_bf16_f32 v152, v56, v57
	v_cvt_pk_bf16_f32 v153, v58, v59
	v_cvt_pk_bf16_f32 v154, v60, v61
	v_cvt_pk_bf16_f32 v155, v62, v63
	s_nop 1
	v_mfma_f32_32x32x16_bf16 v[16:31], v[148:151], v[152:155], v[16:31]
	v_exp_f32_e32 v32, v32
	s_waitcnt lgkmcnt(4)
	v_mfma_f32_32x32x16_bf16 v[0:15], v[144:147], v[152:155], v[0:15]
	v_exp_f32_e32 v33, v33
	v_exp_f32_e32 v34, v34
	v_exp_f32_e32 v35, v35
	v_exp_f32_e32 v36, v36
	v_exp_f32_e32 v37, v37
	v_exp_f32_e32 v38, v38
	v_exp_f32_e32 v39, v39
	v_cvt_pk_bf16_f32 v144, v32, v33
	v_cvt_pk_bf16_f32 v145, v34, v35
	v_cvt_pk_bf16_f32 v146, v36, v37
	v_cvt_pk_bf16_f32 v147, v38, v39
	s_waitcnt lgkmcnt(3)
	s_nop 0
	v_mfma_f32_32x32x16_bf16 v[16:31], v[140:143], v[144:147], v[16:31]
	v_exp_f32_e32 v40, v40
	s_waitcnt lgkmcnt(2)
	v_mfma_f32_32x32x16_bf16 v[0:15], v[136:139], v[144:147], v[0:15]
	v_exp_f32_e32 v41, v41
	v_exp_f32_e32 v42, v42
	v_exp_f32_e32 v43, v43
	v_exp_f32_e32 v44, v44
	v_exp_f32_e32 v45, v45
	v_exp_f32_e32 v46, v46
	v_exp_f32_e32 v47, v47
	v_cvt_pk_bf16_f32 v136, v40, v41
	v_cvt_pk_bf16_f32 v137, v42, v43
	v_cvt_pk_bf16_f32 v138, v44, v45
	v_cvt_pk_bf16_f32 v139, v46, v47
	s_add_i32 s4, s4, 3
	s_cmp_ge_u32 s4, s13
	s_waitcnt lgkmcnt(1)
	v_mfma_f32_32x32x16_bf16 v[16:31], v[128:131], v[136:139], v[16:31]
	s_waitcnt vmcnt(1)
	ds_write_b128 v194, v[112:115] offset:44032
	ds_write_b128 v204, v[108:111] offset:44032
	ds_write_b128 v206, v[116:119] offset:44032
	ds_write_b64 v208, v[120:121] offset:44032
	ds_write_b64 v208, v[122:123] offset:44048
	s_waitcnt vmcnt(0)
	ds_write_b64 v208, v[124:125] offset:52736
	ds_write_b64 v208, v[126:127] offset:52752
	s_waitcnt lgkmcnt(0)
	s_barrier
	v_mfma_f32_32x32x16_bf16 v[0:15], v[132:135], v[136:139], v[0:15]
	ds_read_b128 v[238:241], v210 offset:44032
	ds_read_b128 v[128:131], v210 offset:44064
	ds_read_b128 v[132:135], v210 offset:44096
	ds_read_b128 v[136:139], v210 offset:44128
	ds_read_b128 v[140:143], v210 offset:44160
	ds_read_b128 v[144:147], v210 offset:44192
	ds_read_b128 v[242:245], v210 offset:50688
	ds_read_b128 v[148:151], v210 offset:50720
	ds_read_b128 v[152:155], v210 offset:50752
	ds_read_b128 v[156:159], v210 offset:50784
	ds_read_b128 v[214:217], v210 offset:50816
	ds_read_b128 v[234:237], v210 offset:50848
	s_cbranch_scc1 .LBB0_803
	v_lshl_add_u64 v[108:109], s[94:95], 0, v[174:175]
	v_add_co_u32_e32 v108, vcc, 0x18b2e000, v108
	v_lshl_add_u64 v[110:111], s[94:95], 0, v[172:173]
	s_nop 0
	v_addc_co_u32_e32 v109, vcc, 0, v109, vcc
	v_add_co_u32_e32 v110, vcc, 0x18b2e000, v110
	v_lshl_add_u64 v[116:117], s[94:95], 0, v[170:171]
	s_nop 0
	v_addc_co_u32_e32 v111, vcc, 0, v111, vcc
	v_add_co_u32_e32 v116, vcc, 0x18b2e000, v116
	v_lshl_add_u64 v[120:121], s[94:95], 0, v[166:167]
	s_nop 0
	v_addc_co_u32_e32 v117, vcc, 0, v117, vcc
	v_lshl_add_u64 v[124:125], s[94:95], 0, v[168:169]
	global_load_dwordx4 v[112:115], v[108:109], off
	s_nop 0
	global_load_dwordx4 v[108:111], v[110:111], off
	s_nop 0
	global_load_dwordx4 v[116:119], v[116:117], off
	s_nop 0
	global_load_dwordx4 v[120:123], v[120:121], off
	s_nop 0
	global_load_dwordx4 v[124:127], v[124:125], off
; #define MFMA(a, b, c) __builtin_amdgcn_mfma_f32_32x32x16_bf16((a), (b), (c), 0, 0, 0)
; DI float fexp2(float x) { return __builtin_amdgcn_exp2f(x); }
; DI f32x16 zero16() { f32x16 z; for (int i = 0; i < 16; ++i) z[i] = 0.f; return z; }
; DI void phase_attn(const Params& p, int hf, bool skipctx, char* smem, int& rot) {
;     ...
;       f32x16 st[2]; st[0] = zero16(); st[1] = zero16();
;       {
;         bf16x8 kf[2][6];
; #pragma unroll
;         for (int kb = 0; kb < 2; ++kb)
; #pragma unroll
;           for (int ks = 0; ks < 6; ++ks) kf[kb][ks] = *(const bf16x8*)(sk + (kb * 32 + r) * KROW + (ks * 16 + h * 8) * 2);
;         __builtin_amdgcn_sched_barrier(0);
; #pragma unroll
;         for (int ks = 0; ks < 6; ++ks)
; #pragma unroll
;           for (int kb = 0; kb < 2; ++kb) st[kb] = MFMA(kf[kb][ks], qf[ks], st[kb]);
;         __builtin_amdgcn_sched_barrier(0);
;       }
;       bf16x8 vf[2][2][2];
; #pragma unroll
;       for (int kb = 0; kb < 2; ++kb)
; #pragma unroll
;         for (int s2 = 0; s2 < 2; ++s2)
; #pragma unroll
;           for (int dvb = 0; dvb < 2; ++dvb) {
;             const char* vp = sv + (dvb * 32 + r) * VROW + (kb * 32 + 16 * s2 + 4 * h) * 2;
;             const s16x4 lo = *(const s16x4*)vp, hi = *(const s16x4*)(vp + 16);
;             vf[kb][s2][dvb] = __builtin_shufflevector(lo, hi, 0, 1, 2, 3, 4, 5, 6, 7);
;           }
;       float mx = st[0][0];
; #pragma unroll
;       for (int i = 0; i < 16; ++i) { mx = fmaxf(mx, st[0][i]); mx = fmaxf(mx, st[1][i]); }
;       if (__any(mx > m_run + 8.f)) {
;         mx = fmaxf(mx, __shfl_xor(mx, 32));
;         const float m_new = fmaxf(m_run, mx);
;         const float alpha = fexp2(m_run - m_new);
;         m_run = m_new;
;         l_run *= alpha;
; #pragma unroll
;         for (int i = 0; i < 16; ++i) { o[0][i] *= alpha; o[1][i] *= alpha; }
;       }
;       float ps = 0.f;
; #pragma unroll
;       for (int kb = 0; kb < 2; ++kb)
; #pragma unroll
;         for (int i = 0; i < 16; ++i) { const float e = fexp2(st[kb][i] - m_run); st[kb][i] = e; ps += e; }
;       l_run += ps;
.LBB0_803:
	v_add_f32_e32 v48, 0, v48
	v_add_f32_e32 v48, v49, v48
	v_add_f32_e32 v48, v50, v48
	v_add_f32_e32 v48, v51, v48
	v_add_f32_e32 v48, v52, v48
	v_add_f32_e32 v48, v53, v48
	v_add_f32_e32 v48, v54, v48
	v_add_f32_e32 v48, v55, v48
	v_add_f32_e32 v48, v56, v48
	v_add_f32_e32 v48, v57, v48
	v_add_f32_e32 v48, v58, v48
	v_add_f32_e32 v48, v59, v48
	v_add_f32_e32 v48, v60, v48
	v_add_f32_e32 v48, v61, v48
	v_add_f32_e32 v48, v62, v48
	v_add_f32_e32 v48, v63, v48
	v_add_f32_e32 v32, v32, v48
	v_add_f32_e32 v32, v33, v32
	v_add_f32_e32 v32, v34, v32
	v_add_f32_e32 v32, v35, v32
	v_add_f32_e32 v32, v36, v32
	v_add_f32_e32 v32, v37, v32
	v_add_f32_e32 v32, v38, v32
	v_add_f32_e32 v32, v39, v32
	v_add_f32_e32 v32, v40, v32
	v_add_f32_e32 v32, v41, v32
	v_add_f32_e32 v32, v42, v32
	v_add_f32_e32 v32, v43, v32
	v_add_f32_e32 v32, v44, v32
	v_add_f32_e32 v32, v45, v32
	v_add_f32_e32 v32, v46, v32
	v_add_f32_e32 v32, v47, v32
	v_add_f32_e32 v213, v213, v32
	s_waitcnt lgkmcnt(11)
	v_mfma_f32_32x32x16_bf16 v[48:63], v[238:241], v[64:67], v[176:191]
	s_waitcnt lgkmcnt(5)
	v_mfma_f32_32x32x16_bf16 v[32:47], v[242:245], v[64:67], v[176:191]
	v_mfma_f32_32x32x16_bf16 v[48:63], v[128:131], v[68:71], v[48:63]
	s_waitcnt lgkmcnt(4)
	v_mfma_f32_32x32x16_bf16 v[32:47], v[148:151], v[68:71], v[32:47]
	v_mfma_f32_32x32x16_bf16 v[48:63], v[132:135], v[72:75], v[48:63]
	s_waitcnt lgkmcnt(3)
	v_mfma_f32_32x32x16_bf16 v[32:47], v[152:155], v[72:75], v[32:47]
	v_mfma_f32_32x32x16_bf16 v[48:63], v[136:139], v[88:91], v[48:63]
	s_waitcnt lgkmcnt(2)
	v_mfma_f32_32x32x16_bf16 v[32:47], v[156:159], v[88:91], v[32:47]
	v_mfma_f32_32x32x16_bf16 v[48:63], v[140:143], v[96:99], v[48:63]
	s_waitcnt lgkmcnt(1)
	v_mfma_f32_32x32x16_bf16 v[32:47], v[214:217], v[96:99], v[32:47]
	v_mfma_f32_32x32x16_bf16 v[48:63], v[144:147], v[100:103], v[48:63]
	s_waitcnt lgkmcnt(0)
	v_mfma_f32_32x32x16_bf16 v[32:47], v[234:237], v[100:103], v[32:47]
	s_nop 3
	ds_read_b128 v[152:155], v211 offset:52736
	ds_read_b128 v[156:159], v211 offset:44032
	ds_read_b128 v[148:151], v211 offset:44064
	ds_read_b128 v[144:147], v211 offset:52768
	ds_read_b128 v[140:143], v211 offset:44096
	ds_read_b128 v[136:139], v211 offset:52800
	ds_read_b128 v[132:135], v211 offset:44128
	ds_read_b128 v[128:131], v211 offset:52832
	v_max_f32_e32 v195, v32, v32
	v_max_f32_e32 v200, v48, v48
	v_max_f32_e32 v195, v200, v195
	v_max3_f32 v195, v195, v49, v33
	v_max3_f32 v195, v195, v50, v34
	v_max3_f32 v195, v195, v51, v35
	v_max3_f32 v195, v195, v52, v36
	v_max3_f32 v195, v195, v53, v37
	v_max3_f32 v195, v195, v54, v38
	v_max3_f32 v195, v195, v55, v39
	v_max3_f32 v195, v195, v56, v40
	v_max3_f32 v195, v195, v57, v41
	v_max3_f32 v195, v195, v58, v42
	v_max3_f32 v195, v195, v59, v43
	v_max3_f32 v195, v195, v60, v44
	v_max3_f32 v195, v195, v61, v45
	v_max3_f32 v195, v195, v62, v46
	v_max3_f32 v215, v195, v63, v47
	v_cmp_gt_f32_e32 vcc, v215, v220
	s_cbranch_vccz .LBB0_805
	v_sub_f32_e32 v215, v215, v176
	v_cmp_lt_i32_e32 vcc, v224, v207
	s_nop 1
	v_cndmask_b32_e32 v195, v205, v224, vcc
	v_lshlrev_b32_e32 v195, 2, v195
	ds_bpermute_b32 v195, v195, v215
	s_waitcnt lgkmcnt(0)
	v_max3_f32 v195, v212, v215, v195
	v_sub_f32_e32 v200, v212, v195
	v_exp_f32_e32 v200, v200
	v_mov_b32_e32 v212, v195
	v_mul_f32_e32 v213, v213, v200
	v_pk_mul_f32 v[30:31], v[30:31], v[200:201] op_sel_hi:[1,0]
	v_pk_mul_f32 v[28:29], v[28:29], v[200:201] op_sel_hi:[1,0]
	v_pk_mul_f32 v[26:27], v[26:27], v[200:201] op_sel_hi:[1,0]
	v_pk_mul_f32 v[24:25], v[24:25], v[200:201] op_sel_hi:[1,0]
	v_pk_mul_f32 v[22:23], v[22:23], v[200:201] op_sel_hi:[1,0]
	v_pk_mul_f32 v[20:21], v[20:21], v[200:201] op_sel_hi:[1,0]
	v_pk_mul_f32 v[18:19], v[18:19], v[200:201] op_sel_hi:[1,0]
	v_pk_mul_f32 v[16:17], v[16:17], v[200:201] op_sel_hi:[1,0]
	v_pk_mul_f32 v[14:15], v[14:15], v[200:201] op_sel_hi:[1,0]
	v_pk_mul_f32 v[12:13], v[12:13], v[200:201] op_sel_hi:[1,0]
	v_pk_mul_f32 v[10:11], v[10:11], v[200:201] op_sel_hi:[1,0]
	v_pk_mul_f32 v[8:9], v[8:9], v[200:201] op_sel_hi:[1,0]
	v_pk_mul_f32 v[6:7], v[6:7], v[200:201] op_sel_hi:[1,0]
	v_pk_mul_f32 v[4:5], v[4:5], v[200:201] op_sel_hi:[1,0]
	v_pk_mul_f32 v[2:3], v[2:3], v[200:201] op_sel_hi:[1,0]
	v_pk_mul_f32 v[0:1], v[0:1], v[200:201] op_sel_hi:[1,0]
	v_add_f32_e32 v202, v195, v176
	v_sub_f32_e32 v32, v32, v202
	v_sub_f32_e32 v33, v33, v202
	v_sub_f32_e32 v34, v34, v202
	v_sub_f32_e32 v35, v35, v202
	v_sub_f32_e32 v36, v36, v202
	v_sub_f32_e32 v37, v37, v202
	v_sub_f32_e32 v38, v38, v202
	v_sub_f32_e32 v39, v39, v202
	v_sub_f32_e32 v40, v40, v202
	v_sub_f32_e32 v41, v41, v202
	v_sub_f32_e32 v42, v42, v202
	v_sub_f32_e32 v43, v43, v202
	v_sub_f32_e32 v44, v44, v202
	v_sub_f32_e32 v45, v45, v202
	v_sub_f32_e32 v46, v46, v202
	v_sub_f32_e32 v47, v47, v202
	v_sub_f32_e32 v48, v48, v202
	v_sub_f32_e32 v49, v49, v202
	v_sub_f32_e32 v50, v50, v202
	v_sub_f32_e32 v51, v51, v202
	v_sub_f32_e32 v52, v52, v202
	v_sub_f32_e32 v53, v53, v202
	v_sub_f32_e32 v54, v54, v202
	v_sub_f32_e32 v55, v55, v202
	v_sub_f32_e32 v56, v56, v202
	v_sub_f32_e32 v57, v57, v202
	v_sub_f32_e32 v58, v58, v202
	v_sub_f32_e32 v59, v59, v202
	v_sub_f32_e32 v60, v60, v202
	v_sub_f32_e32 v61, v61, v202
	v_sub_f32_e32 v62, v62, v202
	v_sub_f32_e32 v63, v63, v202
	v_sub_f32_e32 v176, 0, v195
	v_sub_f32_e32 v177, 0, v195
	v_sub_f32_e32 v178, 0, v195
	v_sub_f32_e32 v179, 0, v195
	v_sub_f32_e32 v180, 0, v195
	v_sub_f32_e32 v181, 0, v195
	v_sub_f32_e32 v182, 0, v195
	v_sub_f32_e32 v183, 0, v195
	v_sub_f32_e32 v184, 0, v195
	v_sub_f32_e32 v185, 0, v195
	v_sub_f32_e32 v186, 0, v195
	v_sub_f32_e32 v187, 0, v195
	v_sub_f32_e32 v188, 0, v195
	v_sub_f32_e32 v189, 0, v195
	v_sub_f32_e32 v190, 0, v195
	v_sub_f32_e32 v191, 0, v195
	v_mov_b32_e32 v220, 0x41000000
